# retstate: K/V prefetch made unconditional (clamped index) so the vmcnt waits match the true 2-step prefetch distance (on top of widened state stores)
# baseline (speedup 1.0000x reference)
.LBB0_712:
	s_waitcnt vmcnt(15)
	v_lshlrev_b32_e32 v66, 16, v16
	v_and_b32_e32 v67, 0xffff0000, v16
	v_lshlrev_b32_e32 v68, 16, v17
	v_and_b32_e32 v69, 0xffff0000, v17
	v_lshlrev_b32_e32 v70, 16, v18
	v_and_b32_e32 v71, 0xffff0000, v18
	v_lshlrev_b32_e32 v72, 16, v19
	v_and_b32_e32 v73, 0xffff0000, v19
	v_mul_f32_e32 v66, v103, v66
	v_mul_f32_e32 v67, v103, v67
	v_mul_f32_e32 v68, v103, v68
	v_mul_f32_e32 v69, v103, v69
	v_mul_f32_e32 v70, v103, v70
	v_mul_f32_e32 v71, v103, v71
	v_mul_f32_e32 v72, v103, v72
	v_mul_f32_e32 v73, v103, v73
	v_cvt_pk_bf16_f32 v66, v66, v67
	v_cvt_pk_bf16_f32 v67, v68, v69
	v_cvt_pk_bf16_f32 v68, v70, v71
	v_cvt_pk_bf16_f32 v69, v72, v73
	v_add_u32_e32 v70, 0, v130
	ds_write_b128 v70, v[66:69]
	s_waitcnt vmcnt(14)
	v_lshlrev_b32_e32 v66, 16, v20
	v_and_b32_e32 v67, 0xffff0000, v20
	v_lshlrev_b32_e32 v68, 16, v21
	v_and_b32_e32 v69, 0xffff0000, v21
	v_lshlrev_b32_e32 v70, 16, v22
	v_and_b32_e32 v71, 0xffff0000, v22
	v_lshlrev_b32_e32 v72, 16, v23
	v_and_b32_e32 v73, 0xffff0000, v23
	v_mul_f32_e32 v66, v139, v66
	v_mul_f32_e32 v67, v139, v67
	v_mul_f32_e32 v68, v139, v68
	v_mul_f32_e32 v69, v139, v69
	v_mul_f32_e32 v70, v139, v70
	v_mul_f32_e32 v71, v139, v71
	v_mul_f32_e32 v72, v139, v72
	v_mul_f32_e32 v73, v139, v73
	v_cvt_pk_bf16_f32 v66, v66, v67
	v_cvt_pk_bf16_f32 v67, v68, v69
	v_cvt_pk_bf16_f32 v68, v70, v71
	v_cvt_pk_bf16_f32 v69, v72, v73
	v_add_u32_e32 v70, 0, v131
	ds_write_b128 v70, v[66:69]
	s_waitcnt vmcnt(13)
	v_lshlrev_b32_e32 v66, 16, v24
	v_and_b32_e32 v67, 0xffff0000, v24
	v_lshlrev_b32_e32 v68, 16, v25
	v_and_b32_e32 v69, 0xffff0000, v25
	v_lshlrev_b32_e32 v70, 16, v26
	v_and_b32_e32 v71, 0xffff0000, v26
	v_lshlrev_b32_e32 v72, 16, v27
	v_and_b32_e32 v73, 0xffff0000, v27
	v_mul_f32_e32 v66, v140, v66
	v_mul_f32_e32 v67, v140, v67
	v_mul_f32_e32 v68, v140, v68
	v_mul_f32_e32 v69, v140, v69
	v_mul_f32_e32 v70, v140, v70
	v_mul_f32_e32 v71, v140, v71
	v_mul_f32_e32 v72, v140, v72
	v_mul_f32_e32 v73, v140, v73
	v_cvt_pk_bf16_f32 v66, v66, v67
	v_cvt_pk_bf16_f32 v67, v68, v69
	v_cvt_pk_bf16_f32 v68, v70, v71
	v_cvt_pk_bf16_f32 v69, v72, v73
	v_add_u32_e32 v70, 0, v132
	ds_write_b128 v70, v[66:69]
	s_waitcnt vmcnt(12)
	v_lshlrev_b32_e32 v66, 16, v28
	v_and_b32_e32 v67, 0xffff0000, v28
	v_lshlrev_b32_e32 v68, 16, v29
	v_and_b32_e32 v69, 0xffff0000, v29
	v_lshlrev_b32_e32 v70, 16, v30
	s_add_i32 s15, s12, -3
	v_and_b32_e32 v71, 0xffff0000, v30
	v_lshlrev_b32_e32 v72, 16, v31
	v_and_b32_e32 v73, 0xffff0000, v31
	v_mul_f32_e32 v66, v141, v66
	v_mul_f32_e32 v67, v141, v67
	v_mul_f32_e32 v68, v141, v68
	v_mul_f32_e32 v69, v141, v69
	v_mul_f32_e32 v70, v141, v70
	v_mul_f32_e32 v71, v141, v71
	v_mul_f32_e32 v72, v141, v72
	v_mul_f32_e32 v73, v141, v73
	v_cvt_pk_bf16_f32 v66, v66, v67
	v_cvt_pk_bf16_f32 v67, v68, v69
	v_cvt_pk_bf16_f32 v68, v70, v71
	v_cvt_pk_bf16_f32 v69, v72, v73
	v_add_u32_e32 v70, 0, v133
	s_cmp_lt_u32 s15, 14
	ds_write_b128 v70, v[66:69]
	s_waitcnt vmcnt(11)
	ds_write_b128 v138, v[42:45] offset:34816
	s_waitcnt vmcnt(10)
	ds_write_b128 v138, v[46:49] offset:52224
	s_waitcnt lgkmcnt(0)
	s_barrier
	s_add_i32 s23, s12, -1
	s_add_i32 s24, s13, 1
	s_and_b64 s[16:17], s[6:7], exec
	s_cselect_b32 s16, s23, s24
	s_min_i32 s16, s16, 15
	s_max_i32 s16, s16, 0
	s_mul_i32 s88, s16, 0x160000
	v_lshl_add_u64 v[24:25], v[108:109], 0, s[88:89]
	v_add_co_u32_e32 v20, vcc, 0x58000, v24
	v_lshl_add_u64 v[42:43], v[110:111], 0, s[88:89]
	s_nop 0
	v_addc_co_u32_e32 v21, vcc, 0, v25, vcc
	v_add_co_u32_e32 v26, vcc, 0xb0000, v24
	global_load_dwordx4 v[16:19], v[24:25], off
	s_nop 0
	global_load_dwordx4 v[20:23], v[20:21], off
	v_addc_co_u32_e32 v27, vcc, 0, v25, vcc
	v_add_co_u32_e32 v28, vcc, 0x108000, v24
	s_nop 1
	v_addc_co_u32_e32 v29, vcc, 0, v25, vcc
	v_add_co_u32_e32 v46, vcc, 0xb0000, v42
	global_load_dwordx4 v[24:27], v[26:27], off
	s_nop 0
	global_load_dwordx4 v[28:31], v[28:29], off
	v_addc_co_u32_e32 v47, vcc, 0, v43, vcc
	global_load_dwordx4 v[42:45], v[42:43], off
	s_nop 0
	global_load_dwordx4 v[46:49], v[46:47], off
.LBB0_714:
	s_add_i32 s23, s13, 3
	s_and_b64 s[16:17], s[6:7], exec
	s_cselect_b32 s16, s15, s23
	s_add_u32 s16, s10, s16
	s_addc_u32 s17, s11, 0
	s_lshl_b64 s[16:17], s[16:17], 15
	v_lshl_add_u64 v[66:67], v[114:115], 0, s[16:17]
	v_cvt_pk_bf16_f32 v68, v0, v1
	v_cvt_pk_bf16_f32 v69, v2, v3
	v_cvt_pk_bf16_f32 v70, v4, v5
	v_cvt_pk_bf16_f32 v71, v6, v7
	v_cvt_pk_bf16_f32 v72, v8, v9
	v_cvt_pk_bf16_f32 v73, v10, v11
	v_cvt_pk_bf16_f32 v74, v12, v13
	v_cvt_pk_bf16_f32 v75, v14, v15
	v_and_b32_e32 v76, 32, v210
	v_lshrrev_b32_e32 v76, 2, v76
	v_mov_b32_e32 v77, 0
	v_lshl_add_u64 v[66:67], v[66:67], 0, v[76:77]
	v_permlane32_swap_b32 v68, v70
	v_permlane32_swap_b32 v69, v71
	v_permlane32_swap_b32 v72, v74
	v_permlane32_swap_b32 v73, v75
	global_store_dwordx4 v[66:67], v[68:71], off
	global_store_dwordx4 v[66:67], v[72:75], off offset:32
	v_mov_b32_e32 v113, v112
	v_pk_mul_f32 v[14:15], v[112:113], v[14:15]
	v_pk_mul_f32 v[12:13], v[112:113], v[12:13]
	v_pk_mul_f32 v[10:11], v[112:113], v[10:11]
	v_pk_mul_f32 v[8:9], v[112:113], v[8:9]
	v_pk_mul_f32 v[6:7], v[112:113], v[6:7]
	v_pk_mul_f32 v[4:5], v[112:113], v[4:5]
	v_pk_mul_f32 v[2:3], v[112:113], v[2:3]
	v_pk_mul_f32 v[0:1], v[116:117], v[0:1]
	ds_read_b64_tr_b16 v[78:79], v119 offset:0
	ds_read_b64_tr_b16 v[80:81], v119 offset:1088
	ds_read_b64_tr_b16 v[74:75], v119 offset:4352
	ds_read_b64_tr_b16 v[76:77], v119 offset:5440
	ds_read_b64_tr_b16 v[70:71], v119 offset:8704
	ds_read_b64_tr_b16 v[72:73], v119 offset:9792
	ds_read_b64_tr_b16 v[66:67], v119 offset:13056
	ds_read_b64_tr_b16 v[68:69], v119 offset:14144
	s_waitcnt lgkmcnt(0)
	ds_read_b64_tr_b16 v[94:95], v120 offset:0
	ds_read_b64_tr_b16 v[96:97], v120 offset:1088
	ds_read_b64_tr_b16 v[90:91], v120 offset:4352
	ds_read_b64_tr_b16 v[92:93], v120 offset:5440
	ds_read_b64_tr_b16 v[86:87], v120 offset:8704
	ds_read_b64_tr_b16 v[88:89], v120 offset:9792
	ds_read_b64_tr_b16 v[82:83], v120 offset:13056
	ds_read_b64_tr_b16 v[84:85], v120 offset:14144
	s_waitcnt lgkmcnt(0)
	s_waitcnt vmcnt(15)
	v_lshlrev_b32_e32 v105, 16, v34
	v_and_b32_e32 v107, 0xffff0000, v34
	v_mfma_f32_32x32x16_bf16 v[0:15], v[78:81], v[94:97], v[0:15]
	v_lshlrev_b32_e32 v142, 16, v35
	v_and_b32_e32 v143, 0xffff0000, v35
	v_lshlrev_b32_e32 v144, 16, v36
	v_and_b32_e32 v145, 0xffff0000, v36
	v_mul_f32_e32 v105, v103, v105
	v_lshlrev_b32_e32 v146, 16, v37
	v_and_b32_e32 v147, 0xffff0000, v37
	v_mfma_f32_32x32x16_bf16 v[0:15], v[74:77], v[90:93], v[0:15]
	v_mul_f32_e32 v107, v103, v107
	v_mul_f32_e32 v148, v103, v142
	v_mul_f32_e32 v143, v103, v143
	v_mul_f32_e32 v144, v103, v144
	v_mul_f32_e32 v145, v103, v145
	v_cvt_pk_bf16_f32 v142, v105, v107
	v_add_u32_e32 v105, s92, v130
	v_mfma_f32_32x32x16_bf16 v[0:15], v[70:73], v[86:89], v[0:15]
	v_mul_f32_e32 v146, v103, v146
	v_mul_f32_e32 v147, v103, v147
	v_cvt_pk_bf16_f32 v143, v148, v143
	v_cvt_pk_bf16_f32 v144, v144, v145
	v_cvt_pk_bf16_f32 v145, v146, v147
	s_waitcnt vmcnt(14)
	v_and_b32_e32 v107, 0xffff0000, v38
	v_lshlrev_b32_e32 v146, 16, v41
	v_mfma_f32_32x32x16_bf16 v[0:15], v[66:69], v[82:85], v[0:15]
	ds_read_b64_tr_b16 v[90:91], v134 offset:0
	ds_read_b64_tr_b16 v[92:93], v134 offset:1088
	ds_read_b64_tr_b16 v[82:83], v134 offset:4352
	ds_read_b64_tr_b16 v[84:85], v134 offset:5440
	ds_read_b64_tr_b16 v[74:75], v134 offset:8704
	ds_read_b64_tr_b16 v[76:77], v134 offset:9792
	ds_read_b64_tr_b16 v[66:67], v134 offset:13056
	ds_read_b64_tr_b16 v[68:69], v134 offset:14144
	s_waitcnt lgkmcnt(0)
	ds_read_b64_tr_b16 v[94:95], v135 offset:0
	ds_read_b64_tr_b16 v[96:97], v135 offset:1088
	ds_read_b64_tr_b16 v[86:87], v135 offset:4352
	ds_read_b64_tr_b16 v[88:89], v135 offset:5440
	ds_read_b64_tr_b16 v[78:79], v135 offset:8704
	ds_read_b64_tr_b16 v[80:81], v135 offset:9792
	ds_read_b64_tr_b16 v[70:71], v135 offset:13056
	ds_read_b64_tr_b16 v[72:73], v135 offset:14144
	s_waitcnt lgkmcnt(0)
	ds_write_b128 v105, v[142:145]
	v_lshlrev_b32_e32 v105, 16, v38
	v_lshlrev_b32_e32 v142, 16, v39
	v_and_b32_e32 v143, 0xffff0000, v39
	v_lshlrev_b32_e32 v144, 16, v40
	v_mfma_f32_32x32x16_bf16 v[0:15], v[90:93], v[94:97], v[0:15]
	v_and_b32_e32 v145, 0xffff0000, v40
	v_mul_f32_e32 v105, v139, v105
	v_and_b32_e32 v147, 0xffff0000, v41
	v_mul_f32_e32 v107, v139, v107
	v_mul_f32_e32 v148, v139, v142
	v_mul_f32_e32 v143, v139, v143
	v_mul_f32_e32 v144, v139, v144
	v_mfma_f32_32x32x16_bf16 v[0:15], v[82:85], v[86:89], v[0:15]
	v_mul_f32_e32 v145, v139, v145
	v_cvt_pk_bf16_f32 v142, v105, v107
	v_add_u32_e32 v105, s92, v131
	v_mul_f32_e32 v146, v139, v146
	v_mul_f32_e32 v147, v139, v147
	v_cvt_pk_bf16_f32 v143, v148, v143
	v_cvt_pk_bf16_f32 v144, v144, v145
	v_mfma_f32_32x32x16_bf16 v[0:15], v[74:77], v[78:81], v[0:15]
	v_cvt_pk_bf16_f32 v145, v146, v147
	ds_write_b128 v105, v[142:145]
	s_waitcnt vmcnt(13)
	v_lshlrev_b32_e32 v105, 16, v50
	v_and_b32_e32 v107, 0xffff0000, v50
	v_lshlrev_b32_e32 v142, 16, v51
	v_and_b32_e32 v143, 0xffff0000, v51
	v_lshlrev_b32_e32 v144, 16, v52
	v_mfma_f32_32x32x16_bf16 v[0:15], v[66:69], v[70:73], v[0:15]
	v_and_b32_e32 v145, 0xffff0000, v52
	v_mul_f32_e32 v105, v140, v105
	v_lshlrev_b32_e32 v146, 16, v53
	v_and_b32_e32 v147, 0xffff0000, v53
	v_mul_f32_e32 v107, v140, v107
	v_mul_f32_e32 v148, v140, v142
	v_mul_f32_e32 v143, v140, v143
	v_mul_f32_e32 v144, v140, v144
	v_mul_f32_e32 v145, v140, v145
	v_cvt_pk_bf16_f32 v142, v105, v107
	v_add_u32_e32 v105, s92, v132
	v_mul_f32_e32 v146, v140, v146
	v_mul_f32_e32 v147, v140, v147
	v_cvt_pk_bf16_f32 v143, v148, v143
	v_cvt_pk_bf16_f32 v144, v144, v145
	v_cvt_pk_bf16_f32 v145, v146, v147
	ds_write_b128 v105, v[142:145]
	s_waitcnt vmcnt(12)
	v_lshlrev_b32_e32 v105, 16, v54
	v_and_b32_e32 v107, 0xffff0000, v54
	v_lshlrev_b32_e32 v142, 16, v55
	v_and_b32_e32 v143, 0xffff0000, v55
	v_lshlrev_b32_e32 v144, 16, v56
	v_and_b32_e32 v145, 0xffff0000, v56
	v_mul_f32_e32 v105, v141, v105
	v_lshlrev_b32_e32 v146, 16, v57
	v_and_b32_e32 v147, 0xffff0000, v57
	v_mul_f32_e32 v107, v141, v107
	v_mul_f32_e32 v148, v141, v142
	v_mul_f32_e32 v143, v141, v143
	v_mul_f32_e32 v144, v141, v144
	v_mul_f32_e32 v145, v141, v145
	v_cvt_pk_bf16_f32 v142, v105, v107
	v_add_u32_e32 v105, s92, v133
	v_mul_f32_e32 v146, v141, v146
	v_mul_f32_e32 v147, v141, v147
	v_cvt_pk_bf16_f32 v143, v148, v143
	v_cvt_pk_bf16_f32 v144, v144, v145
	v_cvt_pk_bf16_f32 v145, v146, v147
	ds_write_b128 v105, v[142:145]
	v_add_u32_e32 v105, 0x19800, v138
	s_cmp_gt_u32 s15, 12
	s_waitcnt vmcnt(11)
	ds_write_b128 v105, v[58:61]
	s_waitcnt vmcnt(10)
	ds_write_b128 v105, v[62:65] offset:17408
	s_waitcnt lgkmcnt(0)
	s_barrier
	s_and_b64 s[16:17], s[6:7], exec
	s_cselect_b32 s16, s12, s13
	s_min_i32 s16, s16, 15
	s_max_i32 s16, s16, 0
	s_mul_i32 s88, s16, 0x160000
	v_lshl_add_u64 v[50:51], v[108:109], 0, s[88:89]
	v_add_co_u32_e32 v38, vcc, 0x58000, v50
	v_lshl_add_u64 v[58:59], v[110:111], 0, s[88:89]
	s_nop 0
	v_addc_co_u32_e32 v39, vcc, 0, v51, vcc
	v_add_co_u32_e32 v52, vcc, 0xb0000, v50
	global_load_dwordx4 v[34:37], v[50:51], off
	s_nop 0
	global_load_dwordx4 v[38:41], v[38:39], off
	v_addc_co_u32_e32 v53, vcc, 0, v51, vcc
	v_add_co_u32_e32 v54, vcc, 0x108000, v50
	s_nop 1
	v_addc_co_u32_e32 v55, vcc, 0, v51, vcc
	v_add_co_u32_e32 v62, vcc, 0xb0000, v58
	global_load_dwordx4 v[50:53], v[52:53], off
	s_nop 0
	global_load_dwordx4 v[54:57], v[54:55], off
	v_addc_co_u32_e32 v63, vcc, 0, v59, vcc
	global_load_dwordx4 v[58:61], v[58:59], off
	s_nop 0
	global_load_dwordx4 v[62:65], v[62:63], off
	s_branch .LBB0_711
